# GLA output unit: the 16 LDS fragment reads of the QD.S MFMA chain issued ahead (15 in flight) with counted lgkmcnt instead of read-wait-mfma
# speedup vs baseline: 1.0117x; 1.0039x over previous
; #define LAS __attribute__((address_space(3)))
; __device__ __forceinline__ float bflo(unsigned w) { return __uint_as_float(w << 16); }
; __device__ __forceinline__ float bfhi(unsigned w) { return __uint_as_float(w & 0xffff0000u); }
; __device__ __forceinline__ bf16* ub_slot(unsigned char* ybase, int unit, int) { return (bf16*)ybase + (size_t)unit * 32768; }
; __device__ __forceinline__ void gla_c_unit(LAS unsigned char* lds, const bf16* QKA, const bf16* VA, const bf16* RA, unsigned char* ws, int xnrow0, bf16* OA, int lchunk, int h, const float* gnorm, int tid) {
;     const int lane = tid & 63, w = __builtin_amdgcn_readfirstlane(tid >> 6), r32 = lane & 31, hi = lane >> 5, g16 = lane >> 4, i16 = lane & 15;
;     LAS float* SSQ = (LAS float*)(lds + G_SSQ);
;     const size_t row0 = (size_t)lchunk * 64; const int unit = lchunk * 4 + h;
; #pragma unroll
;     for (int i = 0; i < 2; ++i) { const int id = tid + 512 * i, row = id >> 4, ch = id & 15; *(LAS u32x4*)(lds + G_QD + row * GP + ch * 16) = *(const u32x4*)(QKA + (row0 + row) * 1024 + h * 128 + ch * 8); }
;     bf16x8 sf[8];
;     { const bf16* up = ub_slot(ws, unit, xnrow0) + (size_t)w * 4096 + lane * 8;
; #pragma unroll
;       for (int f = 0; f < 8; ++f) sf[f] = *(const bf16x8*)(up + f * 512); }
;     u32x2 rwv[2][4];
; #pragma unroll
;     for (int ib = 0; ib < 2; ++ib)
; #pragma unroll
;         for (int rg = 0; rg < 4; ++rg) rwv[ib][rg] = *(const u32x2*)(RA + (row0 + 32 * ib + r32) * 1024 + h * 256 + 32 * w + 4 * hi + 8 * rg);
;     f32x16 oT0, oT1;
;     { const bf16* p0 = VA + (row0 + (2 * w) * 4 + g16) * 1024 + h * 256 + i16 * 16; const bf16* p1 = p0 + 4 * 1024;
;       const u32x4 a0 = *(const u32x4*)p0, a1 = *(const u32x4*)(p0 + 8), c0 = *(const u32x4*)p1, c1 = *(const u32x4*)(p1 + 8);
;       const unsigned aw[8] = {a0.x, a0.y, a0.z, a0.w, a1.x, a1.y, a1.z, a1.w}, cw[8] = {c0.x, c0.y, c0.z, c0.w, c1.x, c1.y, c1.z, c1.w};
; #pragma unroll
;       for (int q = 0; q < 8; ++q) { oT0[2 * q] = bflo(aw[q]); oT0[2 * q + 1] = bfhi(aw[q]); oT1[2 * q] = bflo(cw[q]); oT1[2 * q + 1] = bfhi(cw[q]); } }
;     __syncthreads();
.LBB0_697:
	v_readfirstlane_b32 s21, v59
	s_ashr_i32 s8, s20, 2
	s_ashr_i32 s22, s21, 6
	s_and_b32 s10, s20, 3
	s_ashr_i32 s9, s8, 31
	s_ashr_i32 s23, s22, 31
	s_lshl_b64 s[14:15], s[8:9], 6
	s_lshl_b32 s78, s10, 8
	s_lshl_b64 s[24:25], s[22:23], 13
	s_lshl_b32 s8, s10, 9
	s_add_u32 s23, s2, s8
	s_addc_u32 s27, s3, 0
	s_lshl_b32 s10, s22, 5
	s_ashr_i32 s11, s10, 31
	s_lshl_b64 s[16:17], s[10:11], 1
	s_add_u32 s26, s23, s16
	s_addc_u32 s27, s27, s17
	s_lshl_b32 s22, s22, 3
	s_ashr_i32 s23, s22, 31
	s_add_u32 s22, s14, s22
	s_addc_u32 s23, s15, s23
	v_lshl_add_u64 v[6:7], s[14:15], 0, v[54:55]
	v_lshl_add_u64 v[8:9], s[14:15], 0, v[56:57]
	v_mov_b32_e32 v13, s23
	v_or_b32_e32 v12, s22, v64
	v_lshl_add_u64 v[4:5], v[52:53], 0, s[78:79]
	v_lshlrev_b64 v[6:7], 11, v[6:7]
	v_lshlrev_b64 v[8:9], 11, v[8:9]
	v_lshlrev_b64 v[12:13], 11, v[12:13]
	s_mov_b64 s[18:19], s[90:91]
	v_lshl_add_u64 v[6:7], v[4:5], 0, v[6:7]
	v_lshl_add_u64 v[8:9], v[4:5], 0, v[8:9]
	s_mov_b32 s9, s79
	v_lshl_add_u64 v[12:13], s[12:13], 0, v[12:13]
	global_load_dwordx4 v[4:7], v[6:7], off
	s_nop 0
	global_load_dwordx4 v[8:11], v[8:9], off
	v_lshl_add_u64 v[12:13], v[12:13], 0, s[8:9]
	v_mov_b32_e32 v69, v3
	v_lshl_add_u64 v[20:21], v[12:13], 0, v[68:69]
	v_add_co_u32_e64 v22, s[8:9], s96, v20
	global_load_dwordx4 v[12:15], v[20:21], off
	global_load_dwordx4 v[16:19], v[20:21], off offset:16
	v_addc_co_u32_e64 v23, s[8:9], 0, v21, s[8:9]
	global_load_dwordx4 v[32:35], v[22:23], off
	v_lshl_add_u64 v[20:21], v[20:21], 0, s[86:87]
	global_load_dwordx4 v[44:47], v[20:21], off offset:16
	v_lshl_add_u64 v[20:21], v[66:67], 0, s[24:25]
	global_load_dwordx4 v[48:51], v[20:21], off offset:-4096
	global_load_dwordx4 v[86:89], v[20:21], off offset:-3072
	global_load_dwordx4 v[94:97], v[20:21], off offset:-2048
	s_load_dwordx2 s[8:9], s[18:19], 0x60
	global_load_dwordx4 v[98:101], v[20:21], off offset:-1024
	global_load_dwordx4 v[102:105], v[20:21], off
	global_load_dwordx4 v[106:109], v[20:21], off offset:1024
	global_load_dwordx4 v[40:43], v[20:21], off offset:2048
	global_load_dwordx4 v[36:39], v[20:21], off offset:3072
	v_lshlrev_b32_e32 v2, 1, v60
	v_mov_b32_e32 v23, s15
	v_or_b32_e32 v22, s14, v58
	v_mov_b32_e32 v25, s15
	v_or_b32_e32 v24, s14, v62
	v_lshlrev_b64 v[22:23], 11, v[22:23]
	v_lshl_add_u64 v[20:21], s[26:27], 0, v[2:3]
	v_lshlrev_b64 v[24:25], 11, v[24:25]
	v_lshl_add_u64 v[22:23], v[20:21], 0, v[22:23]
	v_lshl_add_u64 v[20:21], v[20:21], 0, v[24:25]
	global_load_dwordx2 v[92:93], v[22:23], off
	global_load_dwordx2 v[84:85], v[22:23], off offset:16
	global_load_dwordx2 v[82:83], v[22:23], off offset:32
	global_load_dwordx2 v[80:81], v[22:23], off offset:48
	global_load_dwordx2 v[76:77], v[20:21], off
	global_load_dwordx2 v[74:75], v[20:21], off offset:16
	global_load_dwordx2 v[72:73], v[20:21], off offset:32
	global_load_dwordx2 v[70:71], v[20:21], off offset:48
	v_add_u32_e32 v69, 0x2000, v79
	s_waitcnt vmcnt(21)
	ds_write_b128 v63, v[4:7]
	s_waitcnt vmcnt(20)
	ds_write_b128 v65, v[8:11]
	s_waitcnt lgkmcnt(0)
	s_barrier
; #define LAS __attribute__((address_space(3)))
; __device__ __forceinline__ float bflo(unsigned w) { return __uint_as_float(w << 16); }
; __device__ __forceinline__ float bfhi(unsigned w) { return __uint_as_float(w & 0xffff0000u); }
; __device__ __forceinline__ bf16x8 cat8(s16x4 a, s16x4 b) { return (bf16x8){a[0], a[1], a[2], a[3], b[0], b[1], b[2], b[3]}; }
; __device__ __forceinline__ void gla_c_unit(LAS unsigned char* lds, const bf16* QKA, const bf16* VA, const bf16* RA, unsigned char* ws, int xnrow0, bf16* OA, int lchunk, int h, const float* gnorm, int tid) {
;     ...
;       const unsigned aw[8] = {a0.x, a0.y, a0.z, a0.w, a1.x, a1.y, a1.z, a1.w}, cw[8] = {c0.x, c0.y, c0.z, c0.w, c1.x, c1.y, c1.z, c1.w};
; #pragma unroll
;       for (int q = 0; q < 8; ++q) { oT0[2 * q] = bflo(aw[q]); oT0[2 * q + 1] = bfhi(aw[q]); oT1[2 * q] = bflo(cw[q]); oT1[2 * q + 1] = bfhi(cw[q]); } }
;     __syncthreads();
; #pragma unroll
;     for (int db = 0; db < 4; ++db)
; #pragma unroll
;         for (int s2 = 0; s2 < 2; ++s2) { const int dcol = (32 * db + 16 * s2 + 4 * hi) * 2;
;             LAS const unsigned char* p0 = lds + G_QD + r32 * GP + dcol; LAS const unsigned char* p1 = lds + G_QD + (32 + r32) * GP + dcol;
;             const bf16x8 qb0 = cat8(*(const LAS s16x4*)p0, *(const LAS s16x4*)(p0 + 16)), qb1 = cat8(*(const LAS s16x4*)p1, *(const LAS s16x4*)(p1 + 16));
;             oT0 = __builtin_amdgcn_mfma_f32_32x32x16_bf16(sf[db * 2 + s2], qb0, oT0, 0, 0, 0); oT1 = __builtin_amdgcn_mfma_f32_32x32x16_bf16(sf[db * 2 + s2], qb1, oT1, 0, 0, 0); }
;     float ss0 = 0.f, ss1 = 0.f;
; #pragma unroll
;     for (int r = 0; r < 16; ++r) { ss0 += oT0[r] * oT0[r]; ss1 += oT1[r] * oT1[r]; }
;     ss0 += __shfl_xor(ss0, 32); ss1 += __shfl_xor(ss1, 32);
;     if (hi == 0) { SSQ[w * 64 + r32] = ss0; SSQ[w * 64 + 32 + r32] = ss1; }
	ds_read2_b64 v[110:113], v79 offset1:2
	ds_read2_b64 v[218:221], v69 offset0:64 offset1:66
	ds_read2_b64 v[222:225], v79 offset0:4 offset1:6
	ds_read2_b64 v[226:229], v69 offset0:68 offset1:70
	ds_read2_b64 v[230:233], v79 offset0:8 offset1:10
	ds_read2_b64 v[234:237], v69 offset0:72 offset1:74
	ds_read2_b64 v[238:241], v79 offset0:12 offset1:14
	ds_read2_b64 v[242:245], v69 offset0:76 offset1:78
	ds_read2_b64 v[246:249], v79 offset0:16 offset1:18
	ds_read2_b64 v[170:173], v69 offset0:80 offset1:82
	ds_read2_b64 v[174:177], v79 offset0:20 offset1:22
	ds_read2_b64 v[182:185], v69 offset0:84 offset1:86
	ds_read2_b64 v[186:189], v79 offset0:24 offset1:26
	ds_read2_b64 v[190:193], v69 offset0:88 offset1:90
	ds_read2_b64 v[214:217], v79 offset0:28 offset1:30
	s_waitcnt vmcnt(19)
	v_lshlrev_b32_e32 v20, 16, v12
	v_and_b32_e32 v21, 0xffff0000, v12
	v_lshlrev_b32_e32 v22, 16, v13
	v_and_b32_e32 v23, 0xffff0000, v13
	v_lshlrev_b32_e32 v24, 16, v14
	v_and_b32_e32 v25, 0xffff0000, v14
	v_lshlrev_b32_e32 v26, 16, v15
	v_and_b32_e32 v27, 0xffff0000, v15
	s_waitcnt vmcnt(18)
	v_lshlrev_b32_e32 v28, 16, v16
	v_and_b32_e32 v29, 0xffff0000, v16
	v_lshlrev_b32_e32 v30, 16, v17
	s_waitcnt vmcnt(17)
	v_lshlrev_b32_e32 v4, 16, v32
	v_and_b32_e32 v5, 0xffff0000, v32
	v_lshlrev_b32_e32 v6, 16, v33
	v_and_b32_e32 v7, 0xffff0000, v33
	v_lshlrev_b32_e32 v8, 16, v34
	v_and_b32_e32 v9, 0xffff0000, v34
	v_lshlrev_b32_e32 v10, 16, v35
	v_and_b32_e32 v11, 0xffff0000, v35
	v_and_b32_e32 v31, 0xffff0000, v17
	v_lshlrev_b32_e32 v32, 16, v18
	v_and_b32_e32 v33, 0xffff0000, v18
	v_lshlrev_b32_e32 v34, 16, v19
	v_and_b32_e32 v35, 0xffff0000, v19
	s_waitcnt vmcnt(16)
	v_lshlrev_b32_e32 v12, 16, v44
	v_and_b32_e32 v13, 0xffff0000, v44
	s_waitcnt vmcnt(15) lgkmcnt(14)
	v_mfma_f32_32x32x16_bf16 v[20:35], v[48:51], v[110:113], v[20:35]
	ds_read2_b64 v[110:113], v69 offset0:92 offset1:94
	v_lshlrev_b32_e32 v14, 16, v45
	v_and_b32_e32 v15, 0xffff0000, v45
	v_lshlrev_b32_e32 v16, 16, v46
	v_and_b32_e32 v17, 0xffff0000, v46
	v_lshlrev_b32_e32 v18, 16, v47
	v_and_b32_e32 v19, 0xffff0000, v47
	s_waitcnt vmcnt(14) lgkmcnt(13)
	v_mfma_f32_32x32x16_bf16 v[20:35], v[86:89], v[222:225], v[20:35]
	v_mfma_f32_32x32x16_bf16 v[4:19], v[48:51], v[218:221], v[4:19]
	s_waitcnt lgkmcnt(12)
	v_mfma_f32_32x32x16_bf16 v[4:19], v[86:89], v[226:229], v[4:19]
	s_waitcnt vmcnt(13) lgkmcnt(11)
	v_mfma_f32_32x32x16_bf16 v[20:35], v[94:97], v[230:233], v[20:35]
	s_waitcnt lgkmcnt(10)
	v_mfma_f32_32x32x16_bf16 v[4:19], v[94:97], v[234:237], v[4:19]
	s_waitcnt vmcnt(12) lgkmcnt(9)
	v_mfma_f32_32x32x16_bf16 v[20:35], v[98:101], v[238:241], v[20:35]
	s_waitcnt lgkmcnt(8)
	v_mfma_f32_32x32x16_bf16 v[4:19], v[98:101], v[242:245], v[4:19]
	s_waitcnt vmcnt(11) lgkmcnt(7)
	v_mfma_f32_32x32x16_bf16 v[20:35], v[102:105], v[246:249], v[20:35]
	s_waitcnt lgkmcnt(6)
	v_mfma_f32_32x32x16_bf16 v[4:19], v[102:105], v[170:173], v[4:19]
	s_waitcnt vmcnt(10) lgkmcnt(5)
	v_mfma_f32_32x32x16_bf16 v[20:35], v[106:109], v[174:177], v[20:35]
	s_waitcnt lgkmcnt(4)
	v_mfma_f32_32x32x16_bf16 v[4:19], v[106:109], v[182:185], v[4:19]
	s_waitcnt vmcnt(9) lgkmcnt(3)
	v_mfma_f32_32x32x16_bf16 v[20:35], v[40:43], v[186:189], v[20:35]
	s_waitcnt lgkmcnt(2)
	v_mfma_f32_32x32x16_bf16 v[4:19], v[40:43], v[190:193], v[4:19]
	s_waitcnt vmcnt(8) lgkmcnt(1)
	v_mfma_f32_32x32x16_bf16 v[20:35], v[36:39], v[214:217], v[20:35]
	s_waitcnt lgkmcnt(0)
	v_mfma_f32_32x32x16_bf16 v[4:19], v[36:39], v[110:113], v[4:19]
	s_nop 9
	v_mul_f32_e32 v36, v20, v20
	v_fmac_f32_e32 v36, v21, v21
	v_fmac_f32_e32 v36, v22, v22
	v_fmac_f32_e32 v36, v23, v23
	v_fmac_f32_e32 v36, v24, v24
	v_fmac_f32_e32 v36, v25, v25
	v_fmac_f32_e32 v36, v26, v26
	v_mul_f32_e32 v37, v5, v5
	v_fmac_f32_e32 v37, v4, v4
	v_fmac_f32_e32 v37, v6, v6
	v_fmac_f32_e32 v37, v7, v7
	v_fmac_f32_e32 v37, v8, v8
	v_fmac_f32_e32 v37, v9, v9
	v_fmac_f32_e32 v37, v10, v10
	v_fmac_f32_e32 v36, v27, v27
	v_fmac_f32_e32 v37, v11, v11
	v_fmac_f32_e32 v36, v28, v28
	v_fmac_f32_e32 v37, v12, v12
	v_fmac_f32_e32 v36, v29, v29
	v_fmac_f32_e32 v37, v13, v13
	v_fmac_f32_e32 v36, v30, v30
	v_fmac_f32_e32 v37, v14, v14
	v_fmac_f32_e32 v36, v31, v31
	v_fmac_f32_e32 v37, v15, v15
	v_fmac_f32_e32 v36, v32, v32
	v_fmac_f32_e32 v37, v16, v16
	v_fmac_f32_e32 v36, v33, v33
	v_fmac_f32_e32 v37, v17, v17
	v_fmac_f32_e32 v36, v34, v34
	v_fmac_f32_e32 v37, v18, v18
	v_fmac_f32_e32 v36, v35, v35
	v_fmac_f32_e32 v37, v19, v19
	ds_bpermute_b32 v38, v200, v36
	ds_bpermute_b32 v39, v200, v37
	s_and_saveexec_b64 s[18:19], vcc
	s_cbranch_execz .LBB0_696
	s_and_b32 s21, s21, 0x3fffffc0
	s_waitcnt lgkmcnt(0)
	v_add_f32_e32 v37, v37, v39
	v_add_f32_e32 v36, v36, v38
	v_lshl_add_u32 v38, s21, 2, v61
	ds_write2_b32 v38, v36, v37 offset1:32
	s_branch .LBB0_696
